# MLA joint path: softmax row sums (as scalar adds) and bf16 packing scheduled into the P.V MFMA shadows; V fragments double-prefetched
# speedup vs baseline: 1.0165x; 1.0047x over previous
; __device__ __forceinline__ float fast_exp2(float x) { return __builtin_amdgcn_exp2f(x); }
; __device__ __forceinline__ float xhalf_max(float x) { auto rr = __builtin_amdgcn_permlane32_swap(__float_as_uint(x), __float_as_uint(x), false, false); return fmaxf(__uint_as_float(rr[0]), __uint_as_float(rr[1])); }
; template <int D, int DV, int MODE, bool HASBIAS, bool JOINT, bool DEFER, class KA, class VA, class PF, class BF, class VF, class NM, class WS, class CB> ...
;     ...
;             float mx = xhalf_max(fmaxf(max16(s0), max16(s1)));
;             const bool grow = __any(mx > m + RESC_THR);
;             const float mn = grow ? fmaxf(m, mx) : m; float sum0 = 0.f, sum1 = 0.f;
;             if (masked) {
; #pragma unroll
;                 for (int v = 0; v < 16; ++v) { const float p0 = s0[v] > -1e29f ? fast_exp2(s0[v] - mn) : 0.f, p1 = s1[v] > -1e29f ? fast_exp2(s1[v] - mn) : 0.f; s0[v] = p0; s1[v] = p1; sum0 += p0; sum1 += p1; }
;             } else {
; #pragma unroll
;                 for (int v = 0; v < 16; ++v) { const float p0 = fast_exp2(s0[v] - mn), p1 = fast_exp2(s1[v] - mn); s0[v] = p0; s1[v] = p1; sum0 += p0; sum1 += p1; }
;             }
.LBB0_1019:
	v_max_f32_e32 v1, v37, v37
	v_max_f32_e32 v68, v36, v36
	v_max_f32_e32 v1, v68, v1
	v_max3_f32 v68, v39, v40, v41
	v_max3_f32 v1, v1, v38, v42
	v_max3_f32 v68, v68, v44, v45
	v_max3_f32 v1, v1, v43, v46
	v_max3_f32 v68, v68, v48, v49
	v_max3_f32 v1, v1, v47, v68
	v_max_f32_e32 v68, v51, v51
	v_max_f32_e32 v69, v50, v50
	v_max_f32_e32 v68, v69, v68
	v_max3_f32 v69, v52, v53, v54
	v_max3_f32 v70, v55, v56, v57
	v_max3_f32 v69, v69, v58, v59
	v_max3_f32 v70, v70, v60, v61
	v_max_f32_e32 v71, v67, v67
	v_max_f32_e32 v72, v66, v66
	v_max3_f32 v69, v69, v62, v63
	v_max3_f32 v70, v70, v64, v65
	v_max_f32_e32 v71, v72, v71
	v_max3_f32 v69, v69, v70, v71
	v_max3_f32 v1, v1, v68, v69
	v_mov_b32_e32 v68, v1
	s_nop 1
	v_permlane32_swap_b32_e32 v1, v68
	v_max_f32_e32 v68, v68, v68
	v_max_f32_e32 v1, v1, v1
	v_max_f32_e32 v1, v1, v68
	v_add_f32_e32 v68, 0x40c00000, v189
	v_cmp_gt_f32_e32 vcc, v1, v68
	s_cmp_lg_u64 vcc, 0
	s_cselect_b64 s[10:11], -1, 0
	s_cmp_eq_u64 vcc, 0
	v_max_f32_e32 v68, v189, v189
	v_max_f32_e32 v1, v68, v1
	s_cselect_b64 vcc, -1, 0
	v_cndmask_b32_e32 v190, v1, v189, vcc
	v_sub_f32_e32 v68, v36, v190
	v_sub_f32_e32 v69, v52, v190
	v_sub_f32_e32 v70, v37, v190
	v_sub_f32_e32 v71, v53, v190
	v_sub_f32_e32 v72, v38, v190
	v_sub_f32_e32 v73, v54, v190
	v_sub_f32_e32 v74, v39, v190
	v_sub_f32_e32 v75, v55, v190
	v_sub_f32_e32 v76, v40, v190
	v_sub_f32_e32 v77, v56, v190
	v_sub_f32_e32 v78, v41, v190
	v_sub_f32_e32 v79, v57, v190
	v_sub_f32_e32 v80, v42, v190
	v_sub_f32_e32 v81, v58, v190
	v_sub_f32_e32 v82, v43, v190
	v_sub_f32_e32 v83, v59, v190
	v_sub_f32_e32 v168, v44, v190
	v_sub_f32_e32 v169, v60, v190
	v_sub_f32_e32 v176, v45, v190
	v_sub_f32_e32 v177, v61, v190
	v_sub_f32_e32 v178, v46, v190
	v_sub_f32_e32 v179, v62, v190
	v_sub_f32_e32 v192, v47, v190
	v_sub_f32_e32 v193, v63, v190
	v_sub_f32_e32 v194, v48, v190
	v_sub_f32_e32 v195, v64, v190
	v_sub_f32_e32 v196, v49, v190
	v_sub_f32_e32 v197, v65, v190
	v_sub_f32_e32 v198, v50, v190
	v_sub_f32_e32 v199, v66, v190
	v_sub_f32_e32 v200, v51, v190
	v_sub_f32_e32 v201, v67, v190
	v_exp_f32_e32 v151, v68
	v_exp_f32_e32 v150, v69
	v_exp_f32_e32 v157, v70
	v_exp_f32_e32 v156, v71
	v_exp_f32_e32 v153, v72
	v_exp_f32_e32 v152, v73
	v_exp_f32_e32 v161, v74
	v_exp_f32_e32 v160, v75
	v_exp_f32_e32 v155, v76
	v_exp_f32_e32 v154, v77
	v_exp_f32_e32 v165, v78
	v_exp_f32_e32 v164, v79
	v_exp_f32_e32 v159, v80
	v_exp_f32_e32 v158, v81
	v_exp_f32_e32 v167, v82
	v_exp_f32_e32 v166, v83
	v_exp_f32_e32 v69, v168
	v_exp_f32_e32 v68, v169
	v_exp_f32_e32 v75, v176
	v_exp_f32_e32 v74, v177
	v_exp_f32_e32 v71, v178
	v_exp_f32_e32 v70, v179
	v_exp_f32_e32 v79, v192
	v_exp_f32_e32 v78, v193
	v_exp_f32_e32 v73, v194
	v_exp_f32_e32 v72, v195
	v_exp_f32_e32 v81, v196
	v_exp_f32_e32 v80, v197
	v_exp_f32_e32 v77, v198
	v_exp_f32_e32 v76, v199
	v_exp_f32_e32 v83, v200
	v_exp_f32_e32 v82, v201
	s_andn2_b64 vcc, exec, s[16:17]
	s_mov_b64 s[16:17], -1
	s_cbranch_vccnz .LBB0_1021
	s_mov_b64 s[16:17], 0
.LBB0_1021:
	s_andn2_b64 vcc, exec, s[16:17]
	s_cbranch_vccnz .LBB0_1023
	s_mov_b32 s12, 0xefa18f08
	v_cmp_lt_f32_e32 vcc, s12, v36
	s_nop 1
	v_cndmask_b32_e32 v151, 0, v151, vcc
	v_cmp_lt_f32_e32 vcc, s12, v52
	s_nop 1
	v_cndmask_b32_e32 v150, 0, v150, vcc
	v_cmp_lt_f32_e32 vcc, s12, v37
	s_nop 1
	v_cndmask_b32_e32 v157, 0, v157, vcc
	v_cmp_lt_f32_e32 vcc, s12, v53
	s_nop 1
	v_cndmask_b32_e32 v156, 0, v156, vcc
	v_cmp_lt_f32_e32 vcc, s12, v38
	s_nop 1
	v_cndmask_b32_e32 v153, 0, v153, vcc
	v_cmp_lt_f32_e32 vcc, s12, v54
	s_nop 1
	v_cndmask_b32_e32 v152, 0, v152, vcc
	v_cmp_lt_f32_e32 vcc, s12, v39
	s_nop 1
	v_cndmask_b32_e32 v161, 0, v161, vcc
	v_cmp_lt_f32_e32 vcc, s12, v55
	s_nop 1
	v_cndmask_b32_e32 v160, 0, v160, vcc
	v_cmp_lt_f32_e32 vcc, s12, v40
	s_nop 1
	v_cndmask_b32_e32 v155, 0, v155, vcc
	v_cmp_lt_f32_e32 vcc, s12, v56
	s_nop 1
	v_cndmask_b32_e32 v154, 0, v154, vcc
	v_cmp_lt_f32_e32 vcc, s12, v41
	s_nop 1
	v_cndmask_b32_e32 v165, 0, v165, vcc
	v_cmp_lt_f32_e32 vcc, s12, v57
	s_nop 1
	v_cndmask_b32_e32 v164, 0, v164, vcc
	v_cmp_lt_f32_e32 vcc, s12, v42
	s_nop 1
	v_cndmask_b32_e32 v159, 0, v159, vcc
	v_cmp_lt_f32_e32 vcc, s12, v58
	s_nop 1
	v_cndmask_b32_e32 v158, 0, v158, vcc
	v_cmp_lt_f32_e32 vcc, s12, v43
	s_nop 1
	v_cndmask_b32_e32 v167, 0, v167, vcc
	v_cmp_lt_f32_e32 vcc, s12, v59
	s_nop 1
	v_cndmask_b32_e32 v166, 0, v166, vcc
	v_cmp_lt_f32_e32 vcc, s12, v44
	s_nop 1
	v_cndmask_b32_e32 v69, 0, v69, vcc
	v_cmp_lt_f32_e32 vcc, s12, v60
	s_nop 1
	v_cndmask_b32_e32 v68, 0, v68, vcc
	v_cmp_lt_f32_e32 vcc, s12, v45
	s_nop 1
	v_cndmask_b32_e32 v75, 0, v75, vcc
	v_cmp_lt_f32_e32 vcc, s12, v61
	s_nop 1
	v_cndmask_b32_e32 v74, 0, v74, vcc
	v_cmp_lt_f32_e32 vcc, s12, v46
	s_nop 1
	v_cndmask_b32_e32 v71, 0, v71, vcc
	v_cmp_lt_f32_e32 vcc, s12, v62
	s_nop 1
	v_cndmask_b32_e32 v70, 0, v70, vcc
	v_cmp_lt_f32_e32 vcc, s12, v47
	s_nop 1
	v_cndmask_b32_e32 v79, 0, v79, vcc
	v_cmp_lt_f32_e32 vcc, s12, v63
	s_nop 1
	v_cndmask_b32_e32 v78, 0, v78, vcc
	v_cmp_lt_f32_e32 vcc, s12, v48
	s_nop 1
	v_cndmask_b32_e32 v73, 0, v73, vcc
	v_cmp_lt_f32_e32 vcc, s12, v64
	s_nop 1
	v_cndmask_b32_e32 v72, 0, v72, vcc
	v_cmp_lt_f32_e32 vcc, s12, v49
	s_nop 1
	v_cndmask_b32_e32 v81, 0, v81, vcc
	v_cmp_lt_f32_e32 vcc, s12, v65
	s_nop 1
	v_cndmask_b32_e32 v80, 0, v80, vcc
	v_cmp_lt_f32_e32 vcc, s12, v50
	s_nop 1
	v_cndmask_b32_e32 v77, 0, v77, vcc
	v_cmp_lt_f32_e32 vcc, s12, v66
	s_nop 1
	v_cndmask_b32_e32 v76, 0, v76, vcc
	v_cmp_lt_f32_e32 vcc, s12, v51
	s_nop 1
	v_cndmask_b32_e32 v83, 0, v83, vcc
	v_cmp_lt_f32_e32 vcc, s12, v67
	s_nop 1
	v_cndmask_b32_e32 v82, 0, v82, vcc

; __device__ __forceinline__ unsigned cvt_pk_bf16(float lo, float hi) { unsigned r; asm volatile("v_cvt_pk_bf16_f32 %0, %1, %2" : "=v"(r) : "v"(lo), "v"(hi)); return r; }
; #define LAS __attribute__((address_space(3)))
; template <int DV32>
; __device__ __forceinline__ void pv_sub(f32x16 (&o)[DV32], const LAS unsigned char* Vt, int vs, int sub, const f32x16& p, int r32, int hi) {
;     ...
;     for (int kb = 0; kb < 2; ++kb) {
;         u32x4 pw; pw.x = cvt_pk_bf16(p[8 * kb + 0], p[8 * kb + 1]); pw.y = cvt_pk_bf16(p[8 * kb + 2], p[8 * kb + 3]); pw.z = cvt_pk_bf16(p[8 * kb + 4], p[8 * kb + 5]); pw.w = cvt_pk_bf16(p[8 * kb + 6], p[8 * kb + 7]);
;         const bf16x8 pf = __builtin_bit_cast(bf16x8, pw);
; #pragma unroll
;         for (int i = 0; i < DV32; ++i) {
;             const bf16x8 vf = *(const LAS bf16x8*)(Vt + (32 * i + r32) * vs + sub * 64 + kb * 32 + hi * 16);
;             o[i] = __builtin_amdgcn_mfma_f32_32x32x16_bf16(vf, pf, o[i], 0, 0, 0);
;         }
; template <int D, int DV, int MODE, bool HASBIAS, bool JOINT, bool DEFER, class KA, class VA, class PF, class BF, class VF, class NM, class WS, class CB> ...
;     ...
;             l += sum0 + sum1; m = mn;
;             if (MODE == 0) {
;                 if (defer_wave) { pp0 = pack8(s0, 0); pp1 = pack8(s0, 1); pp2 = pack8(s1, 0); pp3 = pack8(s1, 1); pend = vslot; }
;                 else { pv_sub<DV / 32>(o, curv, VS, 0, s0, r32, hi); pv_sub<DV / 32>(o, curv, VS, 1, s1, r32, hi); }
.LBB0_1025:
	v_add_u32_e32 v1, v175, v184
	v_cvt_pk_bf16_f32 v194, v151, v157
	v_cvt_pk_bf16_f32 v195, v153, v161
	ds_read_b128 v[198:201], v1 offset:26624
	ds_read_b128 v[48:51], v1 offset:31232
	v_cvt_pk_bf16_f32 v196, v155, v165
	v_cvt_pk_bf16_f32 v197, v159, v167
	s_mov_b64 s[10:11], 0
	v_add_f32_e32 v168, 0, v150
	v_add_f32_e32 v169, 0, v151
	v_cvt_pk_bf16_f32 v36, v69, v75
	v_add_f32_e32 v168, v156, v168
	v_add_f32_e32 v169, v157, v169
	s_waitcnt lgkmcnt(1)
	v_mfma_f32_32x32x16_bf16 v[4:19], v[198:201], v[194:197], v[4:19]
	ds_read_b128 v[52:55], v1 offset:26656
	ds_read_b128 v[56:59], v1 offset:31264
	v_cvt_pk_bf16_f32 v37, v71, v79
	v_add_f32_e32 v168, v152, v168
	v_add_f32_e32 v169, v153, v169
	v_cvt_pk_bf16_f32 v38, v73, v81
	v_add_f32_e32 v168, v160, v168
	v_add_f32_e32 v169, v161, v169
	s_waitcnt lgkmcnt(2)
	v_mfma_f32_32x32x16_bf16 v[20:35], v[48:51], v[194:197], v[20:35]
	v_cvt_pk_bf16_f32 v39, v77, v83
	v_add_f32_e32 v168, v154, v168
	v_add_f32_e32 v169, v155, v169
	v_cvt_pk_bf16_f32 v40, v150, v156
	v_add_f32_e32 v168, v164, v168
	v_add_f32_e32 v169, v165, v169
	s_waitcnt lgkmcnt(1)
	v_mfma_f32_32x32x16_bf16 v[4:19], v[52:55], v[36:39], v[4:19]
	ds_read_b128 v[60:63], v1 offset:26688
	ds_read_b128 v[64:67], v1 offset:31296
	v_cvt_pk_bf16_f32 v41, v152, v160
	v_add_f32_e32 v168, v158, v168
	v_add_f32_e32 v169, v159, v169
	v_cvt_pk_bf16_f32 v42, v154, v164
	v_add_f32_e32 v168, v166, v168
	v_add_f32_e32 v169, v167, v169
	s_waitcnt lgkmcnt(2)
	v_mfma_f32_32x32x16_bf16 v[20:35], v[56:59], v[36:39], v[20:35]
	v_cvt_pk_bf16_f32 v43, v158, v166
	v_add_f32_e32 v168, v68, v168
	v_add_f32_e32 v169, v69, v169
	v_cvt_pk_bf16_f32 v44, v68, v74
	v_add_f32_e32 v168, v74, v168
	v_add_f32_e32 v169, v75, v169
	s_waitcnt lgkmcnt(1)
	v_mfma_f32_32x32x16_bf16 v[4:19], v[60:63], v[40:43], v[4:19]
	ds_read_b128 v[198:201], v1 offset:26720
	ds_read_b128 v[48:51], v1 offset:31328
	v_cvt_pk_bf16_f32 v45, v70, v78
	v_add_f32_e32 v168, v70, v168
	v_add_f32_e32 v169, v71, v169
	v_cvt_pk_bf16_f32 v46, v72, v80
	v_add_f32_e32 v168, v78, v168
	v_add_f32_e32 v169, v79, v169
	s_waitcnt lgkmcnt(2)
	v_mfma_f32_32x32x16_bf16 v[20:35], v[64:67], v[40:43], v[20:35]
	v_cvt_pk_bf16_f32 v47, v76, v82
	v_add_f32_e32 v168, v72, v168
	v_add_f32_e32 v169, v73, v169
	v_add_f32_e32 v168, v80, v168
	v_add_f32_e32 v169, v81, v169
	s_waitcnt lgkmcnt(1)
	v_mfma_f32_32x32x16_bf16 v[4:19], v[198:201], v[44:47], v[4:19]
	v_add_f32_e32 v168, v76, v168
	v_add_f32_e32 v169, v77, v169
	v_add_f32_e32 v168, v82, v168
	v_add_f32_e32 v169, v83, v169
	s_waitcnt lgkmcnt(0)
	v_mfma_f32_32x32x16_bf16 v[20:35], v[48:51], v[44:47], v[20:35]
	v_add_f32_e32 v168, v168, v169
	v_add_f32_e32 v192, v168, v192

; __device__ __forceinline__ float fast_exp2(float x) { return __builtin_amdgcn_exp2f(x); }
; __device__ __forceinline__ float xhalf_max(float x) { auto rr = __builtin_amdgcn_permlane32_swap(__float_as_uint(x), __float_as_uint(x), false, false); return fmaxf(__uint_as_float(rr[0]), __uint_as_float(rr[1])); }
; template <int D, int DV, int MODE, bool HASBIAS, bool JOINT, bool DEFER, class KA, class VA, class PF, class BF, class VF, class NM, class WS, class CB> ...
;     ...
;             float mx = xhalf_max(fmaxf(max16(s0), max16(s1)));
;             const bool grow = __any(mx > m + RESC_THR);
;             const float mn = grow ? fmaxf(m, mx) : m; float sum0 = 0.f, sum1 = 0.f;
;             if (masked) {
; #pragma unroll
;                 for (int v = 0; v < 16; ++v) { const float p0 = s0[v] > -1e29f ? fast_exp2(s0[v] - mn) : 0.f, p1 = s1[v] > -1e29f ? fast_exp2(s1[v] - mn) : 0.f; s0[v] = p0; s1[v] = p1; sum0 += p0; sum1 += p1; }
;             } else {
; #pragma unroll
;                 for (int v = 0; v < 16; ++v) { const float p0 = fast_exp2(s0[v] - mn), p1 = fast_exp2(s1[v] - mn); s0[v] = p0; s1[v] = p1; sum0 += p0; sum1 += p1; }
;             }
.LBB0_1075:
	v_max_f32_e32 v1, v37, v37
	v_max_f32_e32 v68, v36, v36
	v_max_f32_e32 v1, v68, v1
	v_max3_f32 v68, v39, v40, v41
	v_max3_f32 v1, v1, v38, v42
	v_max3_f32 v68, v68, v44, v45
	v_max3_f32 v1, v1, v43, v46
	v_max3_f32 v68, v68, v48, v49
	v_max3_f32 v1, v1, v47, v68
	v_max_f32_e32 v68, v51, v51
	v_max_f32_e32 v69, v50, v50
	v_max_f32_e32 v68, v69, v68
	v_max3_f32 v69, v52, v53, v54
	v_max3_f32 v70, v55, v56, v57
	v_max3_f32 v69, v69, v58, v59
	v_max3_f32 v70, v70, v60, v61
	v_max_f32_e32 v71, v67, v67
	v_max_f32_e32 v72, v66, v66
	v_max3_f32 v69, v69, v62, v63
	v_max3_f32 v70, v70, v64, v65
	v_max_f32_e32 v71, v72, v71
	v_max3_f32 v69, v69, v70, v71
	v_max3_f32 v1, v1, v68, v69
	v_mov_b32_e32 v68, v1
	s_nop 1
	v_permlane32_swap_b32_e32 v1, v68
	v_max_f32_e32 v68, v68, v68
	v_max_f32_e32 v1, v1, v1
	v_max_f32_e32 v1, v1, v68
	v_add_f32_e32 v68, 0x40c00000, v190
	v_cmp_gt_f32_e32 vcc, v1, v68
	s_cmp_lg_u64 vcc, 0
	s_cselect_b64 s[10:11], -1, 0
	s_cmp_eq_u64 vcc, 0
	v_max_f32_e32 v68, v190, v190
	v_max_f32_e32 v1, v68, v1
	s_cselect_b64 vcc, -1, 0
	v_cndmask_b32_e32 v189, v1, v190, vcc
	v_sub_f32_e32 v68, v36, v189
	v_sub_f32_e32 v69, v52, v189
	v_sub_f32_e32 v70, v37, v189
	v_sub_f32_e32 v71, v53, v189
	v_sub_f32_e32 v72, v38, v189
	v_sub_f32_e32 v73, v54, v189
	v_sub_f32_e32 v74, v39, v189
	v_sub_f32_e32 v75, v55, v189
	v_sub_f32_e32 v76, v40, v189
	v_sub_f32_e32 v77, v56, v189
	v_sub_f32_e32 v78, v41, v189
	v_sub_f32_e32 v79, v57, v189
	v_sub_f32_e32 v80, v42, v189
	v_sub_f32_e32 v81, v58, v189
	v_sub_f32_e32 v82, v43, v189
	v_sub_f32_e32 v83, v59, v189
	v_sub_f32_e32 v168, v44, v189
	v_sub_f32_e32 v169, v60, v189
	v_sub_f32_e32 v176, v45, v189
	v_sub_f32_e32 v177, v61, v189
	v_sub_f32_e32 v178, v46, v189
	v_sub_f32_e32 v179, v62, v189
	v_sub_f32_e32 v191, v47, v189
	v_sub_f32_e32 v193, v63, v189
	v_sub_f32_e32 v194, v48, v189
	v_sub_f32_e32 v195, v64, v189
	v_sub_f32_e32 v196, v49, v189
	v_sub_f32_e32 v197, v65, v189
	v_sub_f32_e32 v198, v50, v189
	v_sub_f32_e32 v199, v66, v189
	v_sub_f32_e32 v200, v51, v189
	v_sub_f32_e32 v201, v67, v189
	v_exp_f32_e32 v151, v68
	v_exp_f32_e32 v150, v69
	v_exp_f32_e32 v157, v70
	v_exp_f32_e32 v156, v71
	v_exp_f32_e32 v153, v72
	v_exp_f32_e32 v152, v73
	v_exp_f32_e32 v161, v74
	v_exp_f32_e32 v160, v75
	v_exp_f32_e32 v155, v76
	v_exp_f32_e32 v154, v77
	v_exp_f32_e32 v165, v78
	v_exp_f32_e32 v164, v79
	v_exp_f32_e32 v159, v80
	v_exp_f32_e32 v158, v81
	v_exp_f32_e32 v167, v82
	v_exp_f32_e32 v166, v83
	v_exp_f32_e32 v69, v168
	v_exp_f32_e32 v68, v169
	v_exp_f32_e32 v75, v176
	v_exp_f32_e32 v74, v177
	v_exp_f32_e32 v71, v178
	v_exp_f32_e32 v70, v179
	v_exp_f32_e32 v79, v191
	v_exp_f32_e32 v78, v193
	v_exp_f32_e32 v73, v194
	v_exp_f32_e32 v72, v195
	v_exp_f32_e32 v81, v196
	v_exp_f32_e32 v80, v197
	v_exp_f32_e32 v77, v198
	v_exp_f32_e32 v76, v199
	v_exp_f32_e32 v83, v200
	v_exp_f32_e32 v82, v201
	s_andn2_b64 vcc, exec, s[16:17]
	s_mov_b64 s[16:17], -1
	s_cbranch_vccnz .LBB0_1077
	s_mov_b64 s[16:17], 0

; __device__ __forceinline__ unsigned cvt_pk_bf16(float lo, float hi) { unsigned r; asm volatile("v_cvt_pk_bf16_f32 %0, %1, %2" : "=v"(r) : "v"(lo), "v"(hi)); return r; }
; #define LAS __attribute__((address_space(3)))
; template <int DV32>
; __device__ __forceinline__ void pv_sub(f32x16 (&o)[DV32], const LAS unsigned char* Vt, int vs, int sub, const f32x16& p, int r32, int hi) {
;     ...
;     for (int kb = 0; kb < 2; ++kb) {
;         u32x4 pw; pw.x = cvt_pk_bf16(p[8 * kb + 0], p[8 * kb + 1]); pw.y = cvt_pk_bf16(p[8 * kb + 2], p[8 * kb + 3]); pw.z = cvt_pk_bf16(p[8 * kb + 4], p[8 * kb + 5]); pw.w = cvt_pk_bf16(p[8 * kb + 6], p[8 * kb + 7]);
;         const bf16x8 pf = __builtin_bit_cast(bf16x8, pw);
; #pragma unroll
;         for (int i = 0; i < DV32; ++i) {
;             const bf16x8 vf = *(const LAS bf16x8*)(Vt + (32 * i + r32) * vs + sub * 64 + kb * 32 + hi * 16);
;             o[i] = __builtin_amdgcn_mfma_f32_32x32x16_bf16(vf, pf, o[i], 0, 0, 0);
;         }
; template <int D, int DV, int MODE, bool HASBIAS, bool JOINT, bool DEFER, class KA, class VA, class PF, class BF, class VF, class NM, class WS, class CB> ...
;     ...
;             l += sum0 + sum1; m = mn;
;             if (MODE == 0) {
;                 if (defer_wave) { pp0 = pack8(s0, 0); pp1 = pack8(s0, 1); pp2 = pack8(s1, 0); pp3 = pack8(s1, 1); pend = vslot; }
;                 else { pv_sub<DV / 32>(o, curv, VS, 0, s0, r32, hi); pv_sub<DV / 32>(o, curv, VS, 1, s1, r32, hi); }
.LBB0_1081:
	v_add_u32_e32 v1, v175, v184
	v_cvt_pk_bf16_f32 v194, v151, v157
	v_cvt_pk_bf16_f32 v195, v153, v161
	ds_read_b128 v[198:201], v1 offset:35840
	ds_read_b128 v[48:51], v1 offset:40448
	v_cvt_pk_bf16_f32 v196, v155, v165
	v_cvt_pk_bf16_f32 v197, v159, v167
	s_mov_b64 s[10:11], 0
	v_add_f32_e32 v168, 0, v150
	v_add_f32_e32 v169, 0, v151
	v_cvt_pk_bf16_f32 v36, v69, v75
	v_add_f32_e32 v168, v156, v168
	v_add_f32_e32 v169, v157, v169
	s_waitcnt lgkmcnt(1)
	v_mfma_f32_32x32x16_bf16 v[4:19], v[198:201], v[194:197], v[4:19]
	ds_read_b128 v[52:55], v1 offset:35872
	ds_read_b128 v[56:59], v1 offset:40480
	v_cvt_pk_bf16_f32 v37, v71, v79
	v_add_f32_e32 v168, v152, v168
	v_add_f32_e32 v169, v153, v169
	v_cvt_pk_bf16_f32 v38, v73, v81
	v_add_f32_e32 v168, v160, v168
	v_add_f32_e32 v169, v161, v169
	s_waitcnt lgkmcnt(2)
	v_mfma_f32_32x32x16_bf16 v[20:35], v[48:51], v[194:197], v[20:35]
	v_cvt_pk_bf16_f32 v39, v77, v83
	v_add_f32_e32 v168, v154, v168
	v_add_f32_e32 v169, v155, v169
	v_cvt_pk_bf16_f32 v40, v150, v156
	v_add_f32_e32 v168, v164, v168
	v_add_f32_e32 v169, v165, v169
	s_waitcnt lgkmcnt(1)
	v_mfma_f32_32x32x16_bf16 v[4:19], v[52:55], v[36:39], v[4:19]
	ds_read_b128 v[60:63], v1 offset:35904
	ds_read_b128 v[64:67], v1 offset:40512
	v_cvt_pk_bf16_f32 v41, v152, v160
	v_add_f32_e32 v168, v158, v168
	v_add_f32_e32 v169, v159, v169
	v_cvt_pk_bf16_f32 v42, v154, v164
	v_add_f32_e32 v168, v166, v168
	v_add_f32_e32 v169, v167, v169
	s_waitcnt lgkmcnt(2)
	v_mfma_f32_32x32x16_bf16 v[20:35], v[56:59], v[36:39], v[20:35]
	v_cvt_pk_bf16_f32 v43, v158, v166
	v_add_f32_e32 v168, v68, v168
	v_add_f32_e32 v169, v69, v169
	v_cvt_pk_bf16_f32 v44, v68, v74
	v_add_f32_e32 v168, v74, v168
	v_add_f32_e32 v169, v75, v169
	s_waitcnt lgkmcnt(1)
	v_mfma_f32_32x32x16_bf16 v[4:19], v[60:63], v[40:43], v[4:19]
	ds_read_b128 v[198:201], v1 offset:35936
	ds_read_b128 v[48:51], v1 offset:40544
	v_cvt_pk_bf16_f32 v45, v70, v78
	v_add_f32_e32 v168, v70, v168
	v_add_f32_e32 v169, v71, v169
	v_cvt_pk_bf16_f32 v46, v72, v80
	v_add_f32_e32 v168, v78, v168
	v_add_f32_e32 v169, v79, v169
	s_waitcnt lgkmcnt(2)
	v_mfma_f32_32x32x16_bf16 v[20:35], v[64:67], v[40:43], v[20:35]
	v_cvt_pk_bf16_f32 v47, v76, v82
	v_add_f32_e32 v168, v72, v168
	v_add_f32_e32 v169, v73, v169
	v_add_f32_e32 v168, v80, v168
	v_add_f32_e32 v169, v81, v169
	s_waitcnt lgkmcnt(1)
	v_mfma_f32_32x32x16_bf16 v[4:19], v[198:201], v[44:47], v[4:19]
	v_add_f32_e32 v168, v76, v168
	v_add_f32_e32 v169, v77, v169
	v_add_f32_e32 v168, v82, v168
	v_add_f32_e32 v169, v83, v169
	s_waitcnt lgkmcnt(0)
	v_mfma_f32_32x32x16_bf16 v[20:35], v[48:51], v[44:47], v[20:35]
	v_add_f32_e32 v168, v168, v169
	v_add_f32_e32 v191, v168, v191
